# SSD correction item: C Z fragment loads batched and Z2 loaded once per tile, gains hoisted; SSD first-segment epilogue loads batched
# speedup vs baseline: 1.0782x; 1.0119x over previous
.LBB0_598:
	v_lshl_add_u64 v[130:131], s[72:73], 0, v[78:79]
	global_load_dwordx2 v[56:57], v[130:131], off offset:-64
	global_load_dwordx2 v[128:129], v[130:131], off
	global_load_dwordx2 v[246:247], v[130:131], off offset:-32
	global_load_dwordx2 v[248:249], v[130:131], off offset:32
	ds_read2_b64 v[52:55], v225 offset1:4
	s_waitcnt lgkmcnt(0)
	v_lshlrev_b32_e32 v58, 16, v52
	v_and_b32_e32 v59, 0xffff0000, v52
	v_lshlrev_b32_e32 v1, 16, v53
	v_pk_fma_f32 v[58:59], v[100:101], v[58:59], v[44:45]
	s_waitcnt vmcnt(3)
	v_lshlrev_b32_e32 v60, 16, v56
	v_mul_f32_e32 v52, 0xbfb8aa3b, v60
	v_exp_f32_e32 v52, v52
	v_and_b32_e32 v61, 0xffff0000, v56
	v_lshlrev_b32_e32 v120, 16, v57
	s_waitcnt vmcnt(2)
	v_lshlrev_b32_e32 v132, 16, v128
	v_add_f32_e32 v52, 1.0, v52
	v_rcp_f32_e32 v62, v52
	v_mul_f32_e32 v52, 0xbfb8aa3b, v61
	v_exp_f32_e32 v52, v52
	v_and_b32_e32 v133, 0xffff0000, v128
	v_lshlrev_b32_e32 v226, 16, v129
	v_add_f32_e32 v52, 1.0, v52
	v_rcp_f32_e32 v63, v52
	v_mul_f32_e32 v52, v0, v1
	v_mul_f32_e32 v1, 0xbfb8aa3b, v120
	v_exp_f32_e32 v1, v1
	v_pk_mul_f32 v[60:61], v[62:63], v[60:61]
	v_add_f32_e32 v1, 1.0, v1
	v_rcp_f32_e32 v1, v1
	v_pk_mul_f32 v[118:119], v[58:59], v[60:61]
	v_and_b32_e32 v59, 0xffff0000, v57
	v_and_b32_e32 v58, 0xffff0000, v53
	v_mul_f32_e32 v56, v1, v120
	v_mul_f32_e32 v1, 0xbfb8aa3b, v59
	v_exp_f32_e32 v1, v1
	v_lshlrev_b32_e32 v60, 16, v54
	v_and_b32_e32 v61, 0xffff0000, v54
	v_pk_fma_f32 v[60:61], v[100:101], v[60:61], v[48:49]
	v_add_f32_e32 v1, 1.0, v1
	v_rcp_f32_e32 v1, v1
	s_nop 0
	v_pk_mul_f32 v[58:59], v[0:1], v[58:59]
	s_nop 0
	v_mov_b32_e32 v53, v58
	v_pk_add_f32 v[52:53], v[46:47], v[52:53]
	v_mov_b32_e32 v57, v59
	v_pk_mul_f32 v[120:121], v[52:53], v[56:57]
	s_waitcnt vmcnt(1)
	v_mov_b64_e32 v[52:53], v[246:247]
	v_lshlrev_b32_e32 v1, 16, v55
	v_pk_mul_f32 v[56:57], v[118:119], v[118:119]
	v_pk_mul_f32 v[58:59], v[120:121], v[120:121]
	v_add_f32_e32 v56, v56, v57
	v_add_f32_e32 v57, v58, v59
	v_add_f32_e32 v56, v56, v57
	v_lshlrev_b32_e32 v62, 16, v52
	v_and_b32_e32 v63, 0xffff0000, v52
	v_mul_f32_e32 v52, 0xbfb8aa3b, v62
	v_exp_f32_e32 v52, v52
	v_lshlrev_b32_e32 v124, 16, v53
	v_add_f32_e32 v52, 1.0, v52
	v_rcp_f32_e32 v122, v52
	v_mul_f32_e32 v52, 0xbfb8aa3b, v63
	v_exp_f32_e32 v52, v52
	s_nop 0
	v_add_f32_e32 v52, 1.0, v52
	v_rcp_f32_e32 v123, v52
	v_mul_f32_e32 v52, v0, v1
	v_mul_f32_e32 v1, 0xbfb8aa3b, v124
	v_exp_f32_e32 v1, v1
	v_pk_mul_f32 v[62:63], v[122:123], v[62:63]
	v_add_f32_e32 v1, 1.0, v1
	v_rcp_f32_e32 v1, v1
	v_pk_mul_f32 v[122:123], v[60:61], v[62:63]
	v_and_b32_e32 v61, 0xffff0000, v53
	v_and_b32_e32 v60, 0xffff0000, v55
	v_mul_f32_e32 v54, v1, v124
	v_mul_f32_e32 v1, 0xbfb8aa3b, v61
	v_exp_f32_e32 v1, v1
	s_nop 0
	v_add_f32_e32 v1, 1.0, v1
	v_rcp_f32_e32 v1, v1
	s_nop 0
	v_pk_mul_f32 v[60:61], v[0:1], v[60:61]
	s_nop 0
	v_mov_b32_e32 v53, v60
	v_pk_add_f32 v[52:53], v[50:51], v[52:53]
	v_mov_b32_e32 v55, v61
	v_pk_mul_f32 v[124:125], v[52:53], v[54:55]
	ds_read2_b64 v[52:55], v225 offset0:8 offset1:12
	v_pk_mul_f32 v[60:61], v[122:123], v[122:123]
	v_pk_mul_f32 v[62:63], v[124:125], v[124:125]
	s_waitcnt lgkmcnt(0)
	v_lshlrev_b32_e32 v126, 16, v52
	v_and_b32_e32 v127, 0xffff0000, v52
	v_mul_f32_e32 v52, 0xbfb8aa3b, v132
	v_exp_f32_e32 v52, v52
	v_lshlrev_b32_e32 v1, 16, v53
	v_pk_fma_f32 v[126:127], v[100:101], v[126:127], v[36:37]
	v_add_f32_e32 v52, 1.0, v52
	v_rcp_f32_e32 v134, v52
	v_mul_f32_e32 v52, 0xbfb8aa3b, v133
	v_exp_f32_e32 v52, v52
	s_nop 0
	v_add_f32_e32 v52, 1.0, v52
	v_rcp_f32_e32 v135, v52
	v_mul_f32_e32 v52, v0, v1
	v_mul_f32_e32 v1, 0xbfb8aa3b, v226
	v_exp_f32_e32 v1, v1
	v_pk_mul_f32 v[132:133], v[134:135], v[132:133]
	v_add_f32_e32 v1, 1.0, v1
	v_rcp_f32_e32 v1, v1
	v_pk_mul_f32 v[126:127], v[126:127], v[132:133]
	v_and_b32_e32 v133, 0xffff0000, v129
	v_and_b32_e32 v132, 0xffff0000, v53
	v_mul_f32_e32 v128, v1, v226
	v_mul_f32_e32 v1, 0xbfb8aa3b, v133
	v_exp_f32_e32 v1, v1
	s_nop 0
	v_add_f32_e32 v1, 1.0, v1
	v_rcp_f32_e32 v1, v1
	s_nop 0
	v_pk_mul_f32 v[132:133], v[0:1], v[132:133]
	s_nop 0
	v_mov_b32_e32 v53, v132
	v_mov_b32_e32 v129, v133
	s_waitcnt vmcnt(0)
	v_mov_b64_e32 v[132:133], v[248:249]
	v_lshlrev_b32_e32 v130, 16, v54
	v_and_b32_e32 v131, 0xffff0000, v54
	v_lshlrev_b32_e32 v1, 16, v55
	v_pk_fma_f32 v[130:131], v[100:101], v[130:131], v[40:41]
	v_pk_add_f32 v[52:53], v[38:39], v[52:53]
	v_lshlrev_b32_e32 v226, 16, v132
	v_mul_f32_e32 v54, 0xbfb8aa3b, v226
	v_exp_f32_e32 v54, v54
	v_and_b32_e32 v227, 0xffff0000, v132
	v_lshlrev_b32_e32 v242, 16, v133
	v_pk_mul_f32 v[128:129], v[52:53], v[128:129]
	v_add_f32_e32 v54, 1.0, v54
	v_rcp_f32_e32 v228, v54
	v_mul_f32_e32 v54, 0xbfb8aa3b, v227
	v_exp_f32_e32 v54, v54
	v_pk_mul_f32 v[52:53], v[126:127], v[126:127]
	v_pk_mul_f32 v[134:135], v[128:129], v[128:129]
	v_add_f32_e32 v52, v52, v53
	v_add_f32_e32 v54, 1.0, v54
	v_rcp_f32_e32 v229, v54
	v_mul_f32_e32 v54, v0, v1
	v_mul_f32_e32 v1, 0xbfb8aa3b, v242
	v_exp_f32_e32 v1, v1
	v_pk_mul_f32 v[226:227], v[228:229], v[226:227]
	v_add_f32_e32 v53, v134, v135
	v_pk_mul_f32 v[130:131], v[130:131], v[226:227]
	v_add_f32_e32 v1, 1.0, v1
	v_rcp_f32_e32 v1, v1
	v_and_b32_e32 v227, 0xffff0000, v133
	v_and_b32_e32 v226, 0xffff0000, v55
	v_add_f32_e32 v52, v52, v53
	v_mul_f32_e32 v132, v1, v242
	v_mul_f32_e32 v1, 0xbfb8aa3b, v227
	v_exp_f32_e32 v1, v1
	s_nop 0
	v_add_f32_e32 v1, 1.0, v1
	v_rcp_f32_e32 v1, v1
	s_nop 0
	v_pk_mul_f32 v[226:227], v[0:1], v[226:227]
	s_nop 0
	v_mov_b32_e32 v55, v226
	v_pk_add_f32 v[54:55], v[42:43], v[54:55]
	v_mov_b32_e32 v133, v227
	v_add_f32_e32 v1, v60, v61
	v_add_f32_e32 v60, v62, v63
	v_pk_mul_f32 v[132:133], v[54:55], v[132:133]
	v_add_f32_e32 v1, v1, v60
	v_pk_mul_f32 v[54:55], v[130:131], v[130:131]
	v_pk_mul_f32 v[226:227], v[132:133], v[132:133]
	v_add_f32_e32 v1, v56, v1
	v_add_f32_e32 v1, v1, v52
	v_add_f32_e32 v52, v54, v55
	v_add_f32_e32 v53, v226, v227
	v_add_f32_e32 v52, v52, v53
	v_add_f32_e32 v1, v1, v52
	v_xor_b32_e32 v52, 16, v234
	v_add_u32_e32 v53, 64, v224
	v_cmp_lt_i32_e32 vcc, v52, v53
	s_nop 1
	v_cndmask_b32_e32 v52, v234, v52, vcc
	v_lshlrev_b32_e32 v52, 2, v52
	ds_bpermute_b32 v52, v52, v1
	s_waitcnt lgkmcnt(0)
	v_add_f32_e32 v1, v1, v52
	v_xor_b32_e32 v52, 32, v234
	v_cmp_lt_i32_e32 vcc, v52, v53
	s_nop 1
	v_cndmask_b32_e32 v52, v234, v52, vcc
	v_lshlrev_b32_e32 v52, 2, v52
	ds_bpermute_b32 v52, v52, v1
	s_and_saveexec_b64 s[56:57], s[28:29]
	s_cbranch_execz .LBB0_600
	s_waitcnt lgkmcnt(0)
	v_add_f32_e32 v1, v1, v52
	ds_write_b32 v152, v1

.LBB0_606:
	s_nop 2
	ds_read_b128 v[38:41], v196 offset:34816
	v_mov_b32_e32 v1, s0
	ds_read_b32 v36, v1 offset:508
	v_add_u32_e32 v1, v154, v155
	ds_read_b128 v[42:45], v1 offset:62464
	ds_read_b128 v[46:49], v196 offset:34880
	s_waitcnt lgkmcnt(4)
	ds_read_b128 v[50:53], v1 offset:62528
	ds_read_b128 v[54:57], v1 offset:64768
	ds_read_b128 v[58:61], v1 offset:64832
	v_add_u32_e32 v1, v154, v169
	ds_read_b128 v[224:227], v1 offset:62464
	ds_read_b128 v[242:245], v1 offset:62528
	ds_read_b128 v[246:249], v1 offset:64768
	s_waitcnt lgkmcnt(8)
	v_pk_mul_f32 v[30:31], v[30:31], v[36:37] op_sel_hi:[1,0]
	v_pk_mul_f32 v[28:29], v[28:29], v[36:37] op_sel_hi:[1,0]
	v_pk_mul_f32 v[26:27], v[26:27], v[36:37] op_sel_hi:[1,0]
	v_pk_mul_f32 v[24:25], v[24:25], v[36:37] op_sel_hi:[1,0]
	v_pk_mul_f32 v[22:23], v[22:23], v[36:37] op_sel_hi:[1,0]
	v_pk_mul_f32 v[20:21], v[20:21], v[36:37] op_sel_hi:[1,0]
	v_pk_mul_f32 v[6:7], v[6:7], v[36:37] op_sel_hi:[1,0]
	v_pk_mul_f32 v[4:5], v[4:5], v[36:37] op_sel_hi:[1,0]
	s_waitcnt lgkmcnt(7)
	v_mfma_f32_16x16x32_bf16 v[28:31], v[38:41], v[42:45], v[28:31]
	v_mul_f32_e64 v34, v34, v36
	v_mul_f32_e64 v35, v35, v36
	v_pk_mul_f32 v[32:33], v[32:33], v[36:37] op_sel_hi:[1,0]
	v_pk_mul_f32 v[18:19], v[18:19], v[36:37] op_sel_hi:[1,0]
	s_waitcnt lgkmcnt(4)
	v_mfma_f32_16x16x32_bf16 v[24:27], v[38:41], v[54:57], v[24:27]
	v_mul_f32_e64 v16, v16, v36
	v_mul_f32_e64 v17, v17, v36
	v_pk_mul_f32 v[14:15], v[14:15], v[36:37] op_sel_hi:[1,0]
	v_pk_mul_f32 v[12:13], v[12:13], v[36:37] op_sel_hi:[1,0]
	s_waitcnt lgkmcnt(2)
	v_mfma_f32_16x16x32_bf16 v[20:23], v[38:41], v[224:227], v[20:23]
	v_mul_f32_e64 v10, v10, v36
	v_mul_f32_e64 v11, v11, v36
	v_pk_mul_f32 v[8:9], v[8:9], v[36:37] op_sel_hi:[1,0]
	s_andn2_b64 vcc, exec, s[76:77]
	s_waitcnt lgkmcnt(0)
	v_mfma_f32_16x16x32_bf16 v[4:7], v[38:41], v[246:249], v[4:7]
	ds_read_b128 v[38:41], v1 offset:64832
	v_mfma_f32_16x16x32_bf16 v[28:31], v[46:49], v[50:53], v[28:31]
	v_mfma_f32_16x16x32_bf16 v[24:27], v[46:49], v[58:61], v[24:27]
	v_mfma_f32_16x16x32_bf16 v[20:23], v[46:49], v[242:245], v[20:23]
	s_waitcnt lgkmcnt(0)
	v_mfma_f32_16x16x32_bf16 v[4:7], v[46:49], v[38:41], v[4:7]
	ds_read_b128 v[46:49], v196 offset:37120
	s_waitcnt lgkmcnt(0)
	v_mfma_f32_16x16x32_bf16 v[32:35], v[46:49], v[42:45], v[32:35]
	ds_read_b128 v[42:45], v196 offset:37184
	s_waitcnt lgkmcnt(0)
	s_barrier
	v_mfma_f32_16x16x32_bf16 v[16:19], v[46:49], v[54:57], v[16:19]
	v_mfma_f32_16x16x32_bf16 v[12:15], v[46:49], v[224:227], v[12:15]
	v_mfma_f32_16x16x32_bf16 v[8:11], v[46:49], v[246:249], v[8:11]
	v_mfma_f32_16x16x32_bf16 v[32:35], v[42:45], v[50:53], v[32:35]
	v_mfma_f32_16x16x32_bf16 v[16:19], v[42:45], v[58:61], v[16:19]
	v_mfma_f32_16x16x32_bf16 v[12:15], v[42:45], v[242:245], v[12:15]
	v_mfma_f32_16x16x32_bf16 v[8:11], v[42:45], v[38:41], v[8:11]
	s_cbranch_vccnz .LBB0_583
	global_load_dwordx4 v[40:43], v[64:65], off
	global_load_dwordx4 v[52:55], v[64:65], off offset:64
	global_load_dwordx4 v[56:59], v[64:65], off offset:128
	global_load_dwordx4 v[224:227], v[64:65], off offset:192
	ds_read2st64_b32 v[36:37], v153 offset1:1
	s_waitcnt lgkmcnt(0)
	v_add_f32_e32 v1, v36, v37
	v_fmamk_f32 v1, v1, 0x3c000000, v158
	v_cmp_gt_f32_e32 vcc, s75, v1
	v_mul_f32_e32 v36, 0x4b800000, v1
	s_nop 0
	v_cndmask_b32_e32 v1, v1, v36, vcc
	v_rsq_f32_e32 v1, v1
	s_nop 0
	v_mul_f32_e32 v36, 0x45800000, v1
	v_cndmask_b32_e32 v38, v1, v36, vcc
	v_lshl_add_u64 v[36:37], s[72:73], 0, v[76:77]
	v_pk_mul_f32 v[44:45], v[118:119], v[38:39] op_sel_hi:[1,0]
	v_pk_mul_f32 v[242:243], v[120:121], v[38:39] op_sel_hi:[1,0]
	s_waitcnt vmcnt(0)
	v_pk_mul_f32 v[40:41], v[40:41], v[44:45]
	v_pk_mul_f32 v[42:43], v[42:43], v[242:243]
	v_cvt_pk_bf16_f32 v40, v40, v41
	v_cvt_pk_bf16_f32 v41, v42, v43
	global_store_dwordx2 v[36:37], v[40:41], off offset:-64
	v_pk_mul_f32 v[44:45], v[122:123], v[38:39] op_sel_hi:[1,0]
	v_pk_mul_f32 v[242:243], v[124:125], v[38:39] op_sel_hi:[1,0]
	v_pk_mul_f32 v[52:53], v[52:53], v[44:45]
	v_pk_mul_f32 v[54:55], v[54:55], v[242:243]
	v_cvt_pk_bf16_f32 v52, v52, v53
	v_cvt_pk_bf16_f32 v53, v54, v55
	global_store_dwordx2 v[36:37], v[52:53], off offset:-32
	v_pk_mul_f32 v[44:45], v[126:127], v[38:39] op_sel_hi:[1,0]
	v_pk_mul_f32 v[242:243], v[128:129], v[38:39] op_sel_hi:[1,0]
	v_pk_mul_f32 v[56:57], v[56:57], v[44:45]
	v_pk_mul_f32 v[58:59], v[58:59], v[242:243]
	v_cvt_pk_bf16_f32 v56, v56, v57
	v_cvt_pk_bf16_f32 v57, v58, v59
	global_store_dwordx2 v[36:37], v[56:57], off
	v_pk_mul_f32 v[44:45], v[130:131], v[38:39] op_sel_hi:[1,0]
	v_pk_mul_f32 v[242:243], v[132:133], v[38:39] op_sel_hi:[1,0]
	v_pk_mul_f32 v[224:225], v[224:225], v[44:45]
	v_pk_mul_f32 v[226:227], v[226:227], v[242:243]
	v_cvt_pk_bf16_f32 v224, v224, v225
	v_cvt_pk_bf16_f32 v225, v226, v227
	global_store_dwordx2 v[36:37], v[224:225], off offset:32
	s_branch .LBB0_583

.LBB0_985:
	s_lshl_b32 s26, s55, 6
	s_ashr_i32 s27, s26, 31
	s_mul_i32 s5, s20, 0x1100000
	s_mul_hi_i32 s4, s20, 0x1100000
	s_add_u32 s28, s38, s5
	s_addc_u32 s29, s39, s4
	s_lshl_b64 s[36:37], s[30:31], 15
	s_add_u32 s21, s42, s36
	s_addc_u32 s25, s43, s37
	s_and_b64 s[4:5], s[6:7], exec
	s_cselect_b32 s5, s25, 0
	s_cselect_b32 s4, s21, 0
	s_mul_i32 s25, s30, 22
	s_ashr_i32 s31, s22, 31
	s_mul_hi_i32 s21, s30, 22
	s_add_u32 s30, s25, s22
	s_addc_u32 s31, s21, s31
	s_lshl_b64 s[34:35], s[30:31], 1
	s_add_u32 s21, s34, s16
	s_addc_u32 s25, s35, s17
	s_mulk_i32 s25, 0x2100
	s_mul_hi_u32 s34, s21, 0x2100
	s_add_i32 s25, s34, s25
	s_mulk_i32 s21, 0x2100
	s_add_u32 s34, s46, s21
	s_addc_u32 s35, s47, s25
	v_lshlrev_b32_e32 v2, 2, v0
	v_lshl_add_u64 v[14:15], s[34:35], 0, v[2:3]
	v_lshl_add_u64 v[72:73], v[114:115], 0, s[36:37]
	v_mov_b32_e32 v129, v3
	s_lshl_b64 s[30:31], s[30:31], 14
	v_add_co_u32_e32 v18, vcc, s63, v14
	v_lshlrev_b32_e32 v2, 1, v110
	v_lshl_add_u64 v[16:17], v[72:73], 0, v[128:129]
	v_lshl_add_u64 v[12:13], v[108:109], 0, s[30:31]
	v_addc_co_u32_e32 v19, vcc, 0, v15, vcc
	v_lshl_add_u64 v[20:21], s[34:35], 0, v[2:3]
	v_lshlrev_b32_e32 v2, 1, v112
	s_lshl_b32 s21, s54, 6
	global_load_dwordx4 v[4:7], v[16:17], off
	global_load_dwordx4 v[56:59], v[12:13], off
	global_load_dwordx4 v[60:63], v[12:13], off offset:64
	global_load_dwordx4 v[52:55], v[12:13], off offset:128
	global_load_dwordx4 v[8:11], v[12:13], off offset:192
	v_lshl_add_u64 v[20:21], v[20:21], 0, v[2:3]
	global_load_dword v102, v[18:19], off
	global_load_dwordx2 v[148:149], v[20:21], off
	global_load_dwordx2 v[144:145], v[20:21], off offset:32
	global_load_dwordx2 v[140:141], v[20:21], off offset:64
	v_or_b32_e32 v80, s21, v0
	v_mov_b64_e32 v[18:19], s[28:29]
	v_mad_i64_i32 v[22:23], s[28:29], v80, s64, v[18:19]
	s_lshl_b64 s[28:29], s[26:27], 1
	s_nop 0
	v_lshl_add_u64 v[22:23], v[22:23], 0, s[28:29]
	v_lshl_add_u64 v[22:23], v[22:23], 0, v[2:3]
	s_mov_b64 s[34:35], 0x1c00
	v_lshl_add_u64 v[24:25], v[22:23], 0, s[34:35]
	v_add_co_u32_e32 v22, vcc, s66, v22
	global_load_dwordx2 v[136:137], v[20:21], off offset:96
	global_load_dwordx2 v[142:143], v[24:25], off offset:32
	global_load_dwordx2 v[138:139], v[24:25], off offset:64
	global_load_dwordx2 v[104:105], v[24:25], off offset:96
	v_addc_co_u32_e32 v23, vcc, 0, v23, vcc
	v_add_co_u32_e32 v14, vcc, s57, v14
	v_add_u32_e32 v82, s21, v1
	s_nop 0
	v_addc_co_u32_e32 v15, vcc, 0, v15, vcc
	v_add_co_u32_e32 v12, vcc, s65, v12
	global_load_dwordx2 v[150:151], v[22:23], off offset:3072
	global_load_dword v84, v[14:15], off offset:512
	v_addc_co_u32_e32 v13, vcc, 0, v13, vcc
	v_add_co_u32_e32 v14, vcc, s65, v20
	global_load_dwordx4 v[48:51], v[12:13], off
	global_load_dwordx4 v[44:47], v[12:13], off offset:64
	global_load_dwordx4 v[40:43], v[12:13], off offset:128
	global_load_dwordx4 v[36:39], v[12:13], off offset:192
	v_lshl_add_u64 v[12:13], v[20:21], 0, s[80:81]
	v_addc_co_u32_e32 v15, vcc, 0, v21, vcc
	global_load_dwordx2 v[98:99], v[14:15], off offset:512
	global_load_dwordx2 v[94:95], v[12:13], off offset:32
	global_load_dwordx2 v[90:91], v[12:13], off offset:64
	global_load_dwordx2 v[86:87], v[12:13], off offset:96
	global_load_dwordx4 v[20:23], v[16:17], off offset:128
	v_mad_i64_i32 v[18:19], s[30:31], v82, s64, v[18:19]
	global_load_dwordx4 v[12:15], v[16:17], off offset:64
	v_lshl_add_u64 v[18:19], v[18:19], 0, s[28:29]
	v_lshl_add_u64 v[24:25], v[18:19], 0, v[2:3]
	global_load_dwordx4 v[16:19], v[16:17], off offset:192
	v_add_co_u32_e32 v30, vcc, s66, v24
	v_lshl_add_u64 v[28:29], v[24:25], 0, s[34:35]
	s_nop 0
	v_addc_co_u32_e32 v31, vcc, 0, v25, vcc
	global_load_dwordx2 v[100:101], v[30:31], off offset:3072
	global_load_dwordx2 v[96:97], v[28:29], off offset:32
	global_load_dwordx2 v[92:93], v[28:29], off offset:64
	global_load_dwordx2 v[88:89], v[28:29], off offset:96
	v_lshlrev_b32_e32 v30, 1, v106
	v_mov_b32_e32 v31, v3
	v_lshl_add_u64 v[152:153], s[4:5], 0, v[30:31]
	v_mov_b32_e32 v129, v3
	v_mov_b32_e32 v131, v3
	v_mov_b32_e32 v133, v3
	v_mov_b32_e32 v135, v3
	s_cmp_gt_i32 s54, 20
	s_cselect_b64 s[30:31], -1, 0
	s_cmp_gt_i32 s54, 19
	s_cbranch_scc1 .Lsi_third
	v_lshl_add_u64 v[250:251], v[72:73], 0, v[130:131]
	global_load_dwordx4 v[172:175], v[250:251], off
	global_load_dwordx4 v[176:179], v[250:251], off offset:64
	global_load_dwordx4 v[180:183], v[250:251], off offset:128
	global_load_dwordx4 v[184:187], v[250:251], off offset:192
	v_lshl_add_u64 v[228:229], v[72:73], 0, v[132:133]
	global_load_dwordx4 v[188:191], v[228:229], off
	global_load_dwordx4 v[192:195], v[228:229], off offset:64
	global_load_dwordx4 v[196:199], v[228:229], off offset:128
	global_load_dwordx4 v[200:203], v[228:229], off offset:192
	v_lshl_add_u64 v[250:251], v[72:73], 0, v[134:135]
	global_load_dwordx4 v[204:207], v[250:251], off
	global_load_dwordx4 v[208:211], v[250:251], off offset:64
	global_load_dwordx4 v[212:215], v[250:251], off offset:128
	global_load_dwordx4 v[216:219], v[250:251], off offset:192
	s_waitcnt vmcnt(12)
	v_mov_b32_e32 v147, v146
	v_mfma_f32_16x16x32_bf16 v[32:35], v[4:7], v[56:59], 0
	v_mfma_f32_16x16x32_bf16 v[76:79], v[4:7], v[48:51], 0
	v_mfma_f32_16x16x32_bf16 v[32:35], v[12:15], v[60:63], v[32:35]
	v_mfma_f32_16x16x32_bf16 v[76:79], v[12:15], v[44:47], v[76:79]
	v_mfma_f32_16x16x32_bf16 v[32:35], v[20:23], v[52:55], v[32:35]
	v_mfma_f32_16x16x32_bf16 v[76:79], v[20:23], v[40:43], v[76:79]
	v_mfma_f32_16x16x32_bf16 v[32:35], v[16:19], v[8:11], v[32:35]
	v_mfma_f32_16x16x32_bf16 v[16:19], v[16:19], v[36:39], v[76:79]
	s_waitcnt vmcnt(8)
	v_mfma_f32_16x16x32_bf16 v[28:31], v[172:175], v[56:59], 0
	v_mfma_f32_16x16x32_bf16 v[76:79], v[172:175], v[48:51], 0
	v_mfma_f32_16x16x32_bf16 v[28:31], v[176:179], v[60:63], v[28:31]
	v_mfma_f32_16x16x32_bf16 v[76:79], v[176:179], v[44:47], v[76:79]
	v_mfma_f32_16x16x32_bf16 v[28:31], v[180:183], v[52:55], v[28:31]
	v_mfma_f32_16x16x32_bf16 v[76:79], v[180:183], v[40:43], v[76:79]
	v_mfma_f32_16x16x32_bf16 v[28:31], v[184:187], v[8:11], v[28:31]
	v_mfma_f32_16x16x32_bf16 v[12:15], v[184:187], v[36:39], v[76:79]
	s_waitcnt vmcnt(4)
	v_mfma_f32_16x16x32_bf16 v[24:27], v[188:191], v[56:59], 0
	v_mfma_f32_16x16x32_bf16 v[76:79], v[188:191], v[48:51], 0
	v_mfma_f32_16x16x32_bf16 v[24:27], v[192:195], v[60:63], v[24:27]
	v_mfma_f32_16x16x32_bf16 v[76:79], v[192:195], v[44:47], v[76:79]
	v_mfma_f32_16x16x32_bf16 v[24:27], v[196:199], v[52:55], v[24:27]
	v_mfma_f32_16x16x32_bf16 v[76:79], v[196:199], v[40:43], v[76:79]
	v_mfma_f32_16x16x32_bf16 v[24:27], v[200:203], v[8:11], v[24:27]
	v_mfma_f32_16x16x32_bf16 v[4:7], v[200:203], v[36:39], v[76:79]
	s_waitcnt vmcnt(0)
	v_mfma_f32_16x16x32_bf16 v[20:23], v[204:207], v[56:59], 0
	v_mfma_f32_16x16x32_bf16 v[76:79], v[204:207], v[48:51], 0
	v_mfma_f32_16x16x32_bf16 v[20:23], v[208:211], v[60:63], v[20:23]
	v_mfma_f32_16x16x32_bf16 v[76:79], v[208:211], v[44:47], v[76:79]
	v_mfma_f32_16x16x32_bf16 v[20:23], v[212:215], v[52:55], v[20:23]
	v_mfma_f32_16x16x32_bf16 v[76:79], v[212:215], v[40:43], v[76:79]
	v_mfma_f32_16x16x32_bf16 v[20:23], v[216:219], v[8:11], v[20:23]
	v_mfma_f32_16x16x32_bf16 v[8:11], v[216:219], v[36:39], v[76:79]
	s_nop 7
	s_branch .Lsi_done
.Lsi_third:
	v_lshl_add_u64 v[228:229], v[152:153], 0, v[128:129]
	global_load_dwordx4 v[172:175], v[228:229], off
	global_load_dwordx4 v[176:179], v[228:229], off offset:64
	global_load_dwordx4 v[180:183], v[228:229], off offset:128
	global_load_dwordx4 v[184:187], v[228:229], off offset:192
	v_lshl_add_u64 v[250:251], v[72:73], 0, v[130:131]
	global_load_dwordx4 v[188:191], v[250:251], off
	global_load_dwordx4 v[192:195], v[250:251], off offset:64
	global_load_dwordx4 v[196:199], v[250:251], off offset:128
	global_load_dwordx4 v[200:203], v[250:251], off offset:192
	v_lshl_add_u64 v[254:255], v[152:153], 0, v[130:131]
	global_load_dwordx4 v[204:207], v[254:255], off
	global_load_dwordx4 v[208:211], v[254:255], off offset:64
	global_load_dwordx4 v[212:215], v[254:255], off offset:128
	global_load_dwordx4 v[216:219], v[254:255], off offset:192
	v_lshl_add_u64 v[154:155], v[72:73], 0, v[132:133]
	global_load_dwordx4 v[220:223], v[154:155], off
	global_load_dwordx4 v[224:227], v[154:155], off offset:64
	global_load_dwordx4 v[242:245], v[154:155], off offset:128
	global_load_dwordx4 v[246:249], v[154:155], off offset:192
	s_waitcnt vmcnt(12)
	v_mov_b32_e32 v147, v146
	v_mfma_f32_16x16x32_bf16 v[32:35], v[4:7], v[56:59], 0
	v_mfma_f32_16x16x32_bf16 v[64:67], v[172:175], v[56:59], 0
	v_mfma_f32_16x16x32_bf16 v[32:35], v[12:15], v[60:63], v[32:35]
	v_mfma_f32_16x16x32_bf16 v[64:67], v[176:179], v[60:63], v[64:67]
	v_mfma_f32_16x16x32_bf16 v[32:35], v[20:23], v[52:55], v[32:35]
	v_mfma_f32_16x16x32_bf16 v[64:67], v[180:183], v[52:55], v[64:67]
	v_mfma_f32_16x16x32_bf16 v[32:35], v[16:19], v[8:11], v[32:35]
	v_mfma_f32_16x16x32_bf16 v[64:67], v[184:187], v[8:11], v[64:67]
	v_mfma_f32_16x16x32_bf16 v[76:79], v[4:7], v[48:51], 0
	v_mfma_f32_16x16x32_bf16 v[68:71], v[172:175], v[48:51], 0
	v_mfma_f32_16x16x32_bf16 v[76:79], v[12:15], v[44:47], v[76:79]
	v_mfma_f32_16x16x32_bf16 v[68:71], v[176:179], v[44:47], v[68:71]
	v_mfma_f32_16x16x32_bf16 v[76:79], v[20:23], v[40:43], v[76:79]
	v_mfma_f32_16x16x32_bf16 v[68:71], v[180:183], v[40:43], v[68:71]
	v_mfma_f32_16x16x32_bf16 v[16:19], v[16:19], v[36:39], v[76:79]
	v_mfma_f32_16x16x32_bf16 v[68:71], v[184:187], v[36:39], v[68:71]
	v_lshl_add_u64 v[228:229], v[152:153], 0, v[132:133]
	global_load_dwordx4 v[172:175], v[228:229], off
	global_load_dwordx4 v[176:179], v[228:229], off offset:64
	global_load_dwordx4 v[180:183], v[228:229], off offset:128
	global_load_dwordx4 v[184:187], v[228:229], off offset:192
	s_nop 7
	s_and_b64 vcc, exec, s[30:31]
	s_cbranch_vccz .Lsi_c0
	v_pk_fma_f32 v[32:33], v[146:147], v[32:33], v[64:65]
	v_pk_fma_f32 v[34:35], v[146:147], v[34:35], v[66:67]
.Lsi_c0:
	v_pk_fma_f32 v[16:17], v[146:147], v[16:17], v[68:69]
	v_pk_fma_f32 v[18:19], v[146:147], v[18:19], v[70:71]
	s_waitcnt vmcnt(8)
	v_mfma_f32_16x16x32_bf16 v[28:31], v[188:191], v[56:59], 0
	v_mfma_f32_16x16x32_bf16 v[64:67], v[204:207], v[56:59], 0
	v_mfma_f32_16x16x32_bf16 v[28:31], v[192:195], v[60:63], v[28:31]
	v_mfma_f32_16x16x32_bf16 v[64:67], v[208:211], v[60:63], v[64:67]
	v_mfma_f32_16x16x32_bf16 v[28:31], v[196:199], v[52:55], v[28:31]
	v_mfma_f32_16x16x32_bf16 v[64:67], v[212:215], v[52:55], v[64:67]
	v_mfma_f32_16x16x32_bf16 v[28:31], v[200:203], v[8:11], v[28:31]
	v_mfma_f32_16x16x32_bf16 v[64:67], v[216:219], v[8:11], v[64:67]
	v_mfma_f32_16x16x32_bf16 v[76:79], v[188:191], v[48:51], 0
	v_mfma_f32_16x16x32_bf16 v[68:71], v[204:207], v[48:51], 0
	v_mfma_f32_16x16x32_bf16 v[76:79], v[192:195], v[44:47], v[76:79]
	v_mfma_f32_16x16x32_bf16 v[68:71], v[208:211], v[44:47], v[68:71]
	v_mfma_f32_16x16x32_bf16 v[76:79], v[196:199], v[40:43], v[76:79]
	v_mfma_f32_16x16x32_bf16 v[68:71], v[212:215], v[40:43], v[68:71]
	v_mfma_f32_16x16x32_bf16 v[12:15], v[200:203], v[36:39], v[76:79]
	v_mfma_f32_16x16x32_bf16 v[68:71], v[216:219], v[36:39], v[68:71]
	v_lshl_add_u64 v[250:251], v[72:73], 0, v[134:135]
	global_load_dwordx4 v[188:191], v[250:251], off
	global_load_dwordx4 v[192:195], v[250:251], off offset:64
	global_load_dwordx4 v[196:199], v[250:251], off offset:128
	global_load_dwordx4 v[200:203], v[250:251], off offset:192
	v_lshl_add_u64 v[254:255], v[152:153], 0, v[134:135]
	global_load_dwordx4 v[204:207], v[254:255], off
	global_load_dwordx4 v[208:211], v[254:255], off offset:64
	global_load_dwordx4 v[212:215], v[254:255], off offset:128
	global_load_dwordx4 v[216:219], v[254:255], off offset:192
	s_nop 7
	s_and_b64 vcc, exec, s[30:31]
	s_cbranch_vccz .Lsi_c1
	v_pk_fma_f32 v[28:29], v[146:147], v[28:29], v[64:65]
	v_pk_fma_f32 v[30:31], v[146:147], v[30:31], v[66:67]
.Lsi_c1:
	v_pk_fma_f32 v[12:13], v[146:147], v[12:13], v[68:69]
	v_pk_fma_f32 v[14:15], v[146:147], v[14:15], v[70:71]
	s_waitcnt vmcnt(8)
	v_mfma_f32_16x16x32_bf16 v[24:27], v[220:223], v[56:59], 0
	v_mfma_f32_16x16x32_bf16 v[64:67], v[172:175], v[56:59], 0
	v_mfma_f32_16x16x32_bf16 v[24:27], v[224:227], v[60:63], v[24:27]
	v_mfma_f32_16x16x32_bf16 v[64:67], v[176:179], v[60:63], v[64:67]
	v_mfma_f32_16x16x32_bf16 v[24:27], v[242:245], v[52:55], v[24:27]
	v_mfma_f32_16x16x32_bf16 v[64:67], v[180:183], v[52:55], v[64:67]
	v_mfma_f32_16x16x32_bf16 v[24:27], v[246:249], v[8:11], v[24:27]
	v_mfma_f32_16x16x32_bf16 v[64:67], v[184:187], v[8:11], v[64:67]
	v_mfma_f32_16x16x32_bf16 v[76:79], v[220:223], v[48:51], 0
	v_mfma_f32_16x16x32_bf16 v[68:71], v[172:175], v[48:51], 0
	v_mfma_f32_16x16x32_bf16 v[76:79], v[224:227], v[44:47], v[76:79]
	v_mfma_f32_16x16x32_bf16 v[68:71], v[176:179], v[44:47], v[68:71]
	v_mfma_f32_16x16x32_bf16 v[76:79], v[242:245], v[40:43], v[76:79]
	v_mfma_f32_16x16x32_bf16 v[68:71], v[180:183], v[40:43], v[68:71]
	v_mfma_f32_16x16x32_bf16 v[4:7], v[246:249], v[36:39], v[76:79]
	v_mfma_f32_16x16x32_bf16 v[68:71], v[184:187], v[36:39], v[68:71]
	s_nop 7
	s_and_b64 vcc, exec, s[30:31]
	s_cbranch_vccz .Lsi_c2
	v_pk_fma_f32 v[24:25], v[146:147], v[24:25], v[64:65]
	v_pk_fma_f32 v[26:27], v[146:147], v[26:27], v[66:67]
.Lsi_c2:
	v_pk_fma_f32 v[4:5], v[146:147], v[4:5], v[68:69]
	v_pk_fma_f32 v[6:7], v[146:147], v[6:7], v[70:71]
	s_waitcnt vmcnt(0)
	v_mfma_f32_16x16x32_bf16 v[20:23], v[188:191], v[56:59], 0
	v_mfma_f32_16x16x32_bf16 v[64:67], v[204:207], v[56:59], 0
	v_mfma_f32_16x16x32_bf16 v[20:23], v[192:195], v[60:63], v[20:23]
	v_mfma_f32_16x16x32_bf16 v[64:67], v[208:211], v[60:63], v[64:67]
	v_mfma_f32_16x16x32_bf16 v[20:23], v[196:199], v[52:55], v[20:23]
	v_mfma_f32_16x16x32_bf16 v[64:67], v[212:215], v[52:55], v[64:67]
	v_mfma_f32_16x16x32_bf16 v[20:23], v[200:203], v[8:11], v[20:23]
	v_mfma_f32_16x16x32_bf16 v[64:67], v[216:219], v[8:11], v[64:67]
	v_mfma_f32_16x16x32_bf16 v[76:79], v[188:191], v[48:51], 0
	v_mfma_f32_16x16x32_bf16 v[68:71], v[204:207], v[48:51], 0
	v_mfma_f32_16x16x32_bf16 v[76:79], v[192:195], v[44:47], v[76:79]
	v_mfma_f32_16x16x32_bf16 v[68:71], v[208:211], v[44:47], v[68:71]
	v_mfma_f32_16x16x32_bf16 v[76:79], v[196:199], v[40:43], v[76:79]
	v_mfma_f32_16x16x32_bf16 v[68:71], v[212:215], v[40:43], v[68:71]
	v_mfma_f32_16x16x32_bf16 v[8:11], v[200:203], v[36:39], v[76:79]
	v_mfma_f32_16x16x32_bf16 v[68:71], v[216:219], v[36:39], v[68:71]
	s_nop 7
	s_and_b64 vcc, exec, s[30:31]
	s_cbranch_vccz .Lsi_c3
	v_pk_fma_f32 v[20:21], v[146:147], v[20:21], v[64:65]
	v_pk_fma_f32 v[22:23], v[146:147], v[22:23], v[66:67]
.Lsi_c3:
	v_pk_fma_f32 v[8:9], v[146:147], v[8:9], v[68:69]
	v_pk_fma_f32 v[10:11], v[146:147], v[10:11], v[70:71]
.Lsi_done:
	v_lshl_add_u64 v[228:229], s[26:27], 2, v[116:117]
	global_load_dwordx4 v[172:175], v[228:229], off
	global_load_dwordx4 v[176:179], v[228:229], off offset:64
	global_load_dwordx4 v[180:183], v[228:229], off offset:128
	global_load_dwordx4 v[184:187], v[228:229], off offset:192

.LBB0_1005:
	s_or_b64 exec, exec, s[4:5]
	v_lshl_add_u64 v[48:49], s[26:27], 2, v[116:117]
	s_waitcnt lgkmcnt(0)
	s_barrier
	ds_read2st64_b32 v[52:53], v111 offset1:1
	ds_read2st64_b32 v[54:55], v111 offset0:2 offset1:3
	s_ashr_i32 s21, s20, 31
	s_lshl_b64 s[4:5], s[20:21], 22
	v_ashrrev_i32_e32 v81, 31, v80
	v_ashrrev_i32_e32 v83, 31, v82
	s_add_u32 s4, s0, s4
	v_lshlrev_b64 v[56:57], 11, v[80:81]
	v_lshlrev_b64 v[58:59], 11, v[82:83]
	s_addc_u32 s5, s1, s5
	s_waitcnt lgkmcnt(0)
	v_mov_b32_e32 v60, v54
	v_mov_b32_e32 v61, v52
	v_mov_b32_e32 v52, v55
	v_lshl_add_u64 v[56:57], s[4:5], 0, v[56:57]
	v_lshl_add_u64 v[58:59], s[4:5], 0, v[58:59]
	v_pk_add_f32 v[52:53], v[60:61], v[52:53]
	s_brev_b32 s4, 60
	v_pk_fma_f32 v[52:53], v[52:53], s[4:5], v[158:159] op_sel_hi:[1,0,0]
	v_lshl_add_u64 v[54:55], v[58:59], 0, s[28:29]
	v_mul_f32_e32 v58, 0x4b800000, v53
	v_mul_f32_e32 v59, 0x4b800000, v52
	v_cmp_gt_f32_e32 vcc, s75, v53
	v_cmp_gt_f32_e64 s[4:5], s75, v52
	v_lshl_add_u64 v[56:57], v[56:57], 0, s[28:29]
	v_cndmask_b32_e32 v53, v53, v58, vcc
	v_cndmask_b32_e64 v52, v52, v59, s[4:5]
	v_rsq_f32_e32 v58, v53
	v_rsq_f32_e32 v59, v52
	v_lshl_add_u64 v[52:53], v[56:57], 0, v[2:3]
	v_lshl_add_u64 v[54:55], v[54:55], 0, v[2:3]
	v_mul_f32_e32 v2, 0x45800000, v58
	v_mul_f32_e32 v56, 0x45800000, v59
	v_cndmask_b32_e32 v2, v58, v2, vcc
	v_cndmask_b32_e64 v56, v59, v56, s[4:5]
	v_pk_mul_f32 v[32:33], v[32:33], v[2:3] op_sel_hi:[1,0]
	v_pk_mul_f32 v[34:35], v[34:35], v[2:3] op_sel_hi:[1,0]
	v_pk_mul_f32 v[4:5], v[4:5], v[56:57] op_sel_hi:[1,0]
	v_pk_mul_f32 v[6:7], v[6:7], v[56:57] op_sel_hi:[1,0]
	v_pk_mul_f32 v[28:29], v[28:29], v[2:3] op_sel_hi:[1,0]
	v_pk_mul_f32 v[30:31], v[30:31], v[2:3] op_sel_hi:[1,0]
	v_pk_mul_f32 v[24:25], v[24:25], v[2:3] op_sel_hi:[1,0]
	v_pk_mul_f32 v[26:27], v[26:27], v[2:3] op_sel_hi:[1,0]
	v_pk_mul_f32 v[20:21], v[20:21], v[2:3] op_sel_hi:[1,0]
	v_pk_mul_f32 v[22:23], v[22:23], v[2:3] op_sel_hi:[1,0]
	v_pk_mul_f32 v[16:17], v[16:17], v[56:57] op_sel_hi:[1,0]
	v_pk_mul_f32 v[18:19], v[18:19], v[56:57] op_sel_hi:[1,0]
	v_pk_mul_f32 v[12:13], v[12:13], v[56:57] op_sel_hi:[1,0]
	v_pk_mul_f32 v[14:15], v[14:15], v[56:57] op_sel_hi:[1,0]
	s_mov_b64 s[4:5], 0
	s_waitcnt vmcnt(3)
	v_pk_mul_f32 v[32:33], v[172:173], v[32:33]
	v_pk_mul_f32 v[34:35], v[174:175], v[34:35]
	s_waitcnt vmcnt(1)
	v_pk_mul_f32 v[4:5], v[180:181], v[4:5]
	v_pk_mul_f32 v[6:7], v[182:183], v[6:7]
	v_pk_mul_f32 v[28:29], v[176:177], v[28:29]
	v_pk_mul_f32 v[30:31], v[178:179], v[30:31]
	v_pk_mul_f32 v[24:25], v[180:181], v[24:25]
	v_pk_mul_f32 v[26:27], v[182:183], v[26:27]
	s_waitcnt vmcnt(0)
	v_pk_mul_f32 v[20:21], v[184:185], v[20:21]
	v_pk_mul_f32 v[22:23], v[186:187], v[22:23]
	v_pk_mul_f32 v[16:17], v[172:173], v[16:17]
	v_pk_mul_f32 v[18:19], v[174:175], v[18:19]
	v_pk_mul_f32 v[12:13], v[176:177], v[12:13]
	v_pk_mul_f32 v[14:15], v[178:179], v[14:15]
	v_cvt_pk_bf16_f32 v32, v32, v33
	v_cvt_pk_bf16_f32 v33, v34, v35
	v_cvt_pk_bf16_f32 v4, v4, v5
	v_cvt_pk_bf16_f32 v5, v6, v7
	v_cvt_pk_bf16_f32 v28, v28, v29
	v_cvt_pk_bf16_f32 v29, v30, v31
	v_cvt_pk_bf16_f32 v24, v24, v25
	v_cvt_pk_bf16_f32 v25, v26, v27
	v_cvt_pk_bf16_f32 v20, v20, v21
	v_cvt_pk_bf16_f32 v21, v22, v23
	v_cvt_pk_bf16_f32 v16, v16, v17
	v_cvt_pk_bf16_f32 v17, v18, v19
	v_cvt_pk_bf16_f32 v12, v12, v13
	v_cvt_pk_bf16_f32 v13, v14, v15
	global_store_dwordx2 v[52:53], v[32:33], off offset:1024
	global_store_dwordx2 v[52:53], v[28:29], off offset:1056
	global_store_dwordx2 v[52:53], v[24:25], off offset:1088
	global_store_dwordx2 v[52:53], v[20:21], off offset:1120
	global_store_dwordx2 v[54:55], v[16:17], off offset:1024
	global_store_dwordx2 v[54:55], v[12:13], off offset:1056
	global_store_dwordx2 v[54:55], v[4:5], off offset:1088
	v_pk_mul_f32 v[4:5], v[8:9], v[56:57] op_sel_hi:[1,0]
	v_pk_mul_f32 v[6:7], v[10:11], v[56:57] op_sel_hi:[1,0]
	v_pk_mul_f32 v[4:5], v[184:185], v[4:5]
	v_pk_mul_f32 v[6:7], v[186:187], v[6:7]
	v_cvt_pk_bf16_f32 v4, v4, v5
	v_cvt_pk_bf16_f32 v5, v6, v7
	global_store_dwordx2 v[54:55], v[4:5], off offset:1120
	s_barrier
